# add: rotary cos/sin table with reciprocal constants and binary powering (f64, same series); P1 split-K fix-up loads issued up front (32 in flight)
# speedup vs baseline: 1.0057x; 1.0057x over previous
.LBB0_44:
	s_or_b64 exec, exec, s[6:7]
	s_mov_b32 s0, 0x40a00
	v_cmp_gt_i32_e32 vcc, s0, v4
	s_and_saveexec_b64 s[16:17], vcc
	v_readlane_b32 s40, v245, 54
	v_readlane_b32 s41, v245, 55
	v_readlane_b32 s42, v245, 56
	v_readlane_b32 s43, v245, 57
	s_cbranch_execz .LBB0_53
	s_add_u32 s20, s96, 0x100000
	v_and_b32_e32 v14, 0x7f, v208
	s_mov_b32 s24, 0x9e474a89
	s_mov_b32 s26, 0x6dc9c883
	s_mov_b32 s28, 0x54442d18
	s_mov_b32 s30, 0x33145c07
	s_addc_u32 s21, s97, 0
	s_lshl_b32 s2, s33, 9
	s_mov_b64 s[22:23], 0
	s_mov_b32 s25, 0x3fedc2ed
	s_movk_i32 s3, 0x810
	s_mov_b32 s27, 0x3fc45f30
	s_mov_b32 s29, 0xc01921fb
	s_mov_b32 s31, 0xbcb1a626
	s_mov_b32 s19, 0x409ff
	v_mov_b64_e32 v[76:77], 1.0
	v_mov_b64_e32 v[78:79], s[24:25]
	v_and_b32_e32 v80, 1, v14
	v_cmp_ne_u32_e32 vcc, 0, v80
	v_mul_f64 v[82:83], v[76:77], v[78:79]
	s_nop 0
	v_cndmask_b32_e32 v76, v76, v82, vcc
	v_cndmask_b32_e32 v77, v77, v83, vcc
	v_mul_f64 v[78:79], v[78:79], v[78:79]
	v_and_b32_e32 v80, 2, v14
	v_cmp_ne_u32_e32 vcc, 0, v80
	v_mul_f64 v[82:83], v[76:77], v[78:79]
	s_nop 0
	v_cndmask_b32_e32 v76, v76, v82, vcc
	v_cndmask_b32_e32 v77, v77, v83, vcc
	v_mul_f64 v[78:79], v[78:79], v[78:79]
	v_and_b32_e32 v80, 4, v14
	v_cmp_ne_u32_e32 vcc, 0, v80
	v_mul_f64 v[82:83], v[76:77], v[78:79]
	s_nop 0
	v_cndmask_b32_e32 v76, v76, v82, vcc
	v_cndmask_b32_e32 v77, v77, v83, vcc
	v_mul_f64 v[78:79], v[78:79], v[78:79]
	v_and_b32_e32 v80, 8, v14
	v_cmp_ne_u32_e32 vcc, 0, v80
	v_mul_f64 v[82:83], v[76:77], v[78:79]
	s_nop 0
	v_cndmask_b32_e32 v76, v76, v82, vcc
	v_cndmask_b32_e32 v77, v77, v83, vcc
	v_mul_f64 v[78:79], v[78:79], v[78:79]
	v_and_b32_e32 v80, 16, v14
	v_cmp_ne_u32_e32 vcc, 0, v80
	v_mul_f64 v[82:83], v[76:77], v[78:79]
	s_nop 0
	v_cndmask_b32_e32 v76, v76, v82, vcc
	v_cndmask_b32_e32 v77, v77, v83, vcc
	v_mul_f64 v[78:79], v[78:79], v[78:79]
	v_and_b32_e32 v80, 32, v14
	v_cmp_ne_u32_e32 vcc, 0, v80
	v_mul_f64 v[82:83], v[76:77], v[78:79]
	s_nop 0
	v_cndmask_b32_e32 v76, v76, v82, vcc
	v_cndmask_b32_e32 v77, v77, v83, vcc
	v_mul_f64 v[78:79], v[78:79], v[78:79]
	v_and_b32_e32 v80, 64, v14
	v_cmp_ne_u32_e32 vcc, 0, v80
	v_mul_f64 v[82:83], v[76:77], v[78:79]
	s_nop 0
	v_cndmask_b32_e32 v76, v76, v82, vcc
	v_cndmask_b32_e32 v77, v77, v83, vcc
.LBB0_46:
	v_ashrrev_i32_e32 v5, 7, v4
	v_add_u32_e32 v6, 0x37f0, v5
	v_cvt_f64_i32_e32 v[2:3], v5
	v_cvt_f64_u32_e32 v[6:7], v6
	v_cmp_gt_i32_e32 vcc, s3, v5
	s_nop 1
	v_cndmask_b32_e32 v3, v7, v3, vcc
	v_cndmask_b32_e32 v2, v6, v2, vcc
	v_mul_f64 v[0:1], v[2:3], v[76:77]
	v_mul_f64 v[2:3], v[0:1], s[26:27]
	v_rndne_f64_e32 v[2:3], v[2:3]
	v_fmac_f64_e32 v[0:1], s[28:29], v[2:3]
	v_fmac_f64_e32 v[0:1], s[30:31], v[2:3]
	v_mul_f64 v[6:7], v[0:1], -v[0:1]
	v_mov_b64_e32 v[2:3], 1.0
	v_mov_b64_e32 v[10:11], 1.0
	v_mov_b64_e32 v[12:13], v[0:1]
	s_mov_b32 s38, 0x0
	s_mov_b32 s39, 0x3fe00000
	v_mul_f64 v[16:17], v[6:7], s[38:39]
	s_mov_b32 s36, 0x55555555
	s_mov_b32 s37, 0x3fc55555
	v_mul_f64 v[18:19], v[6:7], s[36:37]
	v_fma_f64 v[2:3], v[10:11], v[16:17], v[2:3]
	v_mul_f64 v[10:11], v[10:11], v[16:17]
	v_fma_f64 v[0:1], v[12:13], v[18:19], v[0:1]
	v_mul_f64 v[12:13], v[12:13], v[18:19]
	s_mov_b32 s38, 0x55555555
	s_mov_b32 s39, 0x3fb55555
	v_mul_f64 v[16:17], v[6:7], s[38:39]
	s_mov_b32 s36, 0x9999999a
	s_mov_b32 s37, 0x3fa99999
	v_mul_f64 v[18:19], v[6:7], s[36:37]
	v_fma_f64 v[2:3], v[10:11], v[16:17], v[2:3]
	v_mul_f64 v[10:11], v[10:11], v[16:17]
	v_fma_f64 v[0:1], v[12:13], v[18:19], v[0:1]
	v_mul_f64 v[12:13], v[12:13], v[18:19]
	s_mov_b32 s38, 0x11111111
	s_mov_b32 s39, 0x3fa11111
	v_mul_f64 v[16:17], v[6:7], s[38:39]
	s_mov_b32 s36, 0x18618618
	s_mov_b32 s37, 0x3f986186
	v_mul_f64 v[18:19], v[6:7], s[36:37]
	v_fma_f64 v[2:3], v[10:11], v[16:17], v[2:3]
	v_mul_f64 v[10:11], v[10:11], v[16:17]
	v_fma_f64 v[0:1], v[12:13], v[18:19], v[0:1]
	v_mul_f64 v[12:13], v[12:13], v[18:19]
	s_mov_b32 s38, 0x92492492
	s_mov_b32 s39, 0x3f924924
	v_mul_f64 v[16:17], v[6:7], s[38:39]
	s_mov_b32 s36, 0x1c71c71c
	s_mov_b32 s37, 0x3f8c71c7
	v_mul_f64 v[18:19], v[6:7], s[36:37]
	v_fma_f64 v[2:3], v[10:11], v[16:17], v[2:3]
	v_mul_f64 v[10:11], v[10:11], v[16:17]
	v_fma_f64 v[0:1], v[12:13], v[18:19], v[0:1]
	v_mul_f64 v[12:13], v[12:13], v[18:19]
	s_mov_b32 s38, 0x16c16c17
	s_mov_b32 s39, 0x3f86c16c
	v_mul_f64 v[16:17], v[6:7], s[38:39]
	s_mov_b32 s36, 0x29e4129e
	s_mov_b32 s37, 0x3f829e41
	v_mul_f64 v[18:19], v[6:7], s[36:37]
	v_fma_f64 v[2:3], v[10:11], v[16:17], v[2:3]
	v_mul_f64 v[10:11], v[10:11], v[16:17]
	v_fma_f64 v[0:1], v[12:13], v[18:19], v[0:1]
	v_mul_f64 v[12:13], v[12:13], v[18:19]
	s_mov_b32 s38, 0xf07c1f08
	s_mov_b32 s39, 0x3f7f07c1
	v_mul_f64 v[16:17], v[6:7], s[38:39]
	s_mov_b32 s36, 0x1a41a41a
	s_mov_b32 s37, 0x3f7a41a4
	v_mul_f64 v[18:19], v[6:7], s[36:37]
	v_fma_f64 v[2:3], v[10:11], v[16:17], v[2:3]
	v_mul_f64 v[10:11], v[10:11], v[16:17]
	v_fma_f64 v[0:1], v[12:13], v[18:19], v[0:1]
	v_mul_f64 v[12:13], v[12:13], v[18:19]
	s_mov_b32 s38, 0x16816817
	s_mov_b32 s39, 0x3f768168
	v_mul_f64 v[16:17], v[6:7], s[38:39]
	s_mov_b32 s36, 0x13813814
	s_mov_b32 s37, 0x3f738138
	v_mul_f64 v[18:19], v[6:7], s[36:37]
	v_fma_f64 v[2:3], v[10:11], v[16:17], v[2:3]
	v_mul_f64 v[10:11], v[10:11], v[16:17]
	v_fma_f64 v[0:1], v[12:13], v[18:19], v[0:1]
	v_mul_f64 v[12:13], v[12:13], v[18:19]
	s_mov_b32 s38, 0x11111111
	s_mov_b32 s39, 0x3f711111
	v_mul_f64 v[16:17], v[6:7], s[38:39]
	s_mov_b32 s36, 0x1e1e1e1e
	s_mov_b32 s37, 0x3f6e1e1e
	v_mul_f64 v[18:19], v[6:7], s[36:37]
	v_fma_f64 v[2:3], v[10:11], v[16:17], v[2:3]
	v_mul_f64 v[10:11], v[10:11], v[16:17]
	v_fma_f64 v[0:1], v[12:13], v[18:19], v[0:1]
	v_mul_f64 v[12:13], v[12:13], v[18:19]
	s_mov_b32 s38, 0x1ac5701b
	s_mov_b32 s39, 0x3f6ac570
	v_mul_f64 v[16:17], v[6:7], s[38:39]
	s_mov_b32 s36, 0xfd017f40
	s_mov_b32 s37, 0x3f67f405
	v_mul_f64 v[18:19], v[6:7], s[36:37]
	v_fma_f64 v[2:3], v[10:11], v[16:17], v[2:3]
	v_mul_f64 v[10:11], v[10:11], v[16:17]
	v_fma_f64 v[0:1], v[12:13], v[18:19], v[0:1]
	v_mul_f64 v[12:13], v[12:13], v[18:19]
	s_mov_b32 s38, 0x308158ed
	s_mov_b32 s39, 0x3f658ed2
	v_mul_f64 v[16:17], v[6:7], s[38:39]
	s_mov_b32 s36, 0x13813814
	s_mov_b32 s37, 0x3f638138
	v_mul_f64 v[18:19], v[6:7], s[36:37]
	v_fma_f64 v[2:3], v[10:11], v[16:17], v[2:3]
	v_mul_f64 v[10:11], v[10:11], v[16:17]
	v_fma_f64 v[0:1], v[12:13], v[18:19], v[0:1]
	v_mul_f64 v[12:13], v[12:13], v[18:19]
	s_mov_b32 s38, 0x4046ed29
	s_mov_b32 s39, 0x3f61bb4a
	v_mul_f64 v[16:17], v[6:7], s[38:39]
	s_mov_b32 s36, 0xb51f5e1a
	s_mov_b32 s37, 0x3f603091
	v_mul_f64 v[18:19], v[6:7], s[36:37]
	v_fma_f64 v[2:3], v[10:11], v[16:17], v[2:3]
	v_mul_f64 v[10:11], v[10:11], v[16:17]
	v_fma_f64 v[0:1], v[12:13], v[18:19], v[0:1]
	v_mul_f64 v[12:13], v[12:13], v[18:19]
	s_mov_b32 s38, 0x76b981db
	s_mov_b32 s39, 0x3f5dae60
	v_mul_f64 v[16:17], v[6:7], s[38:39]
	s_mov_b32 s36, 0xb4e81b4f
	s_mov_b32 s37, 0x3f5b4e81
	v_mul_f64 v[18:19], v[6:7], s[36:37]
	v_fma_f64 v[2:3], v[10:11], v[16:17], v[2:3]
	v_mul_f64 v[10:11], v[10:11], v[16:17]
	v_fma_f64 v[0:1], v[12:13], v[18:19], v[0:1]
	v_mul_f64 v[12:13], v[12:13], v[18:19]
	s_mov_b32 s38, 0x7f9b2ce6
	s_mov_b32 s39, 0x3f5934c6
	v_mul_f64 v[16:17], v[6:7], s[38:39]
	s_mov_b32 s36, 0xc201756d
	s_mov_b32 s37, 0x3f5756ca
	v_mul_f64 v[18:19], v[6:7], s[36:37]
	v_fma_f64 v[2:3], v[10:11], v[16:17], v[2:3]
	v_mul_f64 v[10:11], v[10:11], v[16:17]
	v_fma_f64 v[0:1], v[12:13], v[18:19], v[0:1]
	v_mul_f64 v[12:13], v[12:13], v[18:19]
	s_mov_b32 s38, 0x6b015ac0
	s_mov_b32 s39, 0x3f55ac05
	v_mul_f64 v[16:17], v[6:7], s[38:39]
	s_mov_b32 s36, 0x25d51f87
	s_mov_b32 s37, 0x3f542d66
	v_mul_f64 v[18:19], v[6:7], s[36:37]
	v_fma_f64 v[2:3], v[10:11], v[16:17], v[2:3]
	v_mul_f64 v[10:11], v[10:11], v[16:17]
	v_fma_f64 v[0:1], v[12:13], v[18:19], v[0:1]
	v_mul_f64 v[12:13], v[12:13], v[18:19]
	s_mov_b32 s38, 0x12d50a0
	s_mov_b32 s39, 0x3f52d50a
	v_mul_f64 v[16:17], v[6:7], s[38:39]
	s_mov_b32 s36, 0x19e0119e
	s_mov_b32 s37, 0x3f519e01
	v_mul_f64 v[18:19], v[6:7], s[36:37]
	v_fma_f64 v[2:3], v[10:11], v[16:17], v[2:3]
	v_mul_f64 v[10:11], v[10:11], v[16:17]
	v_fma_f64 v[0:1], v[12:13], v[18:19], v[0:1]
	v_mul_f64 v[12:13], v[12:13], v[18:19]
	v_ashrrev_i32_e32 v5, 31, v4
	v_cvt_f32_f64_e32 v1, v[0:1]
	v_cvt_f32_f64_e32 v0, v[2:3]
	v_lshl_add_u64 v[2:3], v[4:5], 3, s[20:21]
	v_add_u32_e32 v4, s2, v4
	v_cmp_lt_i32_e32 vcc, s19, v4
	s_or_b64 s[22:23], vcc, s[22:23]
	global_store_dwordx2 v[2:3], v[0:1], off
	s_andn2_b64 exec, exec, s[22:23]
	s_cbranch_execnz .LBB0_46

.LBB0_388:
	s_add_i32 s4, s7, s16
	s_mul_hi_i32 s7, s4, 0x88888889
	s_add_i32 s7, s7, s4
	s_lshr_b32 s16, s7, 31
	s_ashr_i32 s7, s7, 6
	s_add_i32 s7, s7, s16
	s_lshl_b32 s17, s7, 2
	s_sub_i32 s16, 35, s17
	s_min_i32 s41, s16, 4
	s_abs_i32 s42, s41
	v_cvt_f32_u32_e32 v0, s42
	s_sub_i32 s43, 0, s42
	s_mulk_i32 s7, 0x78
	s_sub_i32 s4, s4, s7
	v_rcp_iflag_f32_e32 v0, v0
	s_abs_i32 s16, s4
	s_xor_b32 s7, s4, s41
	s_ashr_i32 s7, s7, 31
	v_mul_f32_e32 v0, 0x4f7ffffe, v0
	v_cvt_u32_f32_e32 v0, v0
	s_nop 0
	v_readfirstlane_b32 s44, v0
	s_mul_i32 s43, s43, s44
	s_mul_hi_u32 s43, s44, s43
	s_add_i32 s44, s44, s43
	s_mul_hi_u32 s43, s16, s44
	s_mul_i32 s44, s43, s42
	s_sub_i32 s16, s16, s44
	s_add_i32 s44, s43, 1
	s_sub_i32 s45, s16, s42
	s_cmp_ge_u32 s16, s42
	s_cselect_b32 s43, s44, s43
	s_cselect_b32 s16, s45, s16
	s_add_i32 s44, s43, 1
	s_cmp_ge_u32 s16, s42
	s_cselect_b32 s16, s44, s43
	s_xor_b32 s16, s16, s7
	s_sub_i32 s16, s16, s7
	s_mul_i32 s7, s16, s41
	s_sub_i32 s4, s4, s7
	s_ashr_i32 s7, s6, 31
	s_lshl_b64 s[6:7], s[6:7], 21
	v_lshl_add_u64 v[0:1], v[16:17], 0, s[6:7]
	s_bfe_u32 s6, s40, 0x10002
	s_and_b32 s7, s40, 3
	s_add_i32 s17, s17, s4
	s_lshl_b32 s4, s6, 17
	s_lshl_b32 s41, s7, 14
	s_or_b32 s4, s4, s41
	v_lshl_add_u64 v[12:13], v[0:1], 0, s[4:5]
	global_load_dwordx4 v[52:55], v[12:13], off
	s_mov_b32 s4, 0x40000
	v_lshl_add_u64 v[198:199], v[12:13], 0, s[4:5]
	global_load_dwordx4 v[56:59], v[198:199], off
	s_mov_b32 s4, 0x80000
	v_lshl_add_u64 v[196:197], v[12:13], 0, s[4:5]
	global_load_dwordx4 v[60:63], v[196:197], off
	s_mov_b32 s4, 0xc0000
	v_lshl_add_u64 v[198:199], v[12:13], 0, s[4:5]
	global_load_dwordx4 v[64:67], v[198:199], off
	s_mov_b32 s4, 0x100000
	v_lshl_add_u64 v[196:197], v[12:13], 0, s[4:5]
	global_load_dwordx4 v[68:71], v[196:197], off
	s_mov_b32 s4, 0x140000
	v_lshl_add_u64 v[198:199], v[12:13], 0, s[4:5]
	global_load_dwordx4 v[72:75], v[198:199], off
	s_mov_b32 s4, 0x180000
	v_lshl_add_u64 v[196:197], v[12:13], 0, s[4:5]
	global_load_dwordx4 v[76:79], v[196:197], off
	s_mov_b32 s4, 0x1c0000
	v_lshl_add_u64 v[198:199], v[12:13], 0, s[4:5]
	global_load_dwordx4 v[80:83], v[198:199], off
	s_mov_b32 s4, 0x2000
	v_lshl_add_u64 v[196:197], v[12:13], 0, s[4:5]
	global_load_dwordx4 v[84:87], v[196:197], off
	s_mov_b32 s4, 0x42000
	v_lshl_add_u64 v[198:199], v[12:13], 0, s[4:5]
	global_load_dwordx4 v[88:91], v[198:199], off
	s_mov_b32 s4, 0x82000
	v_lshl_add_u64 v[196:197], v[12:13], 0, s[4:5]
	global_load_dwordx4 v[92:95], v[196:197], off
	s_mov_b32 s4, 0xc2000
	v_lshl_add_u64 v[198:199], v[12:13], 0, s[4:5]
	global_load_dwordx4 v[96:99], v[198:199], off
	s_mov_b32 s4, 0x102000
	v_lshl_add_u64 v[196:197], v[12:13], 0, s[4:5]
	global_load_dwordx4 v[100:103], v[196:197], off
	s_mov_b32 s4, 0x142000
	v_lshl_add_u64 v[198:199], v[12:13], 0, s[4:5]
	global_load_dwordx4 v[104:107], v[198:199], off
	s_mov_b32 s4, 0x182000
	v_lshl_add_u64 v[196:197], v[12:13], 0, s[4:5]
	global_load_dwordx4 v[108:111], v[196:197], off
	s_mov_b32 s4, 0x1c2000
	v_lshl_add_u64 v[198:199], v[12:13], 0, s[4:5]
	global_load_dwordx4 v[112:115], v[198:199], off
	s_mov_b32 s4, s3
	v_lshl_add_u64 v[196:197], v[12:13], 0, s[4:5]
	global_load_dwordx4 v[116:119], v[196:197], off
	s_mov_b32 s4, s18
	v_lshl_add_u64 v[198:199], v[12:13], 0, s[4:5]
	global_load_dwordx4 v[120:123], v[198:199], off
	s_mov_b32 s4, s19
	v_lshl_add_u64 v[196:197], v[12:13], 0, s[4:5]
	global_load_dwordx4 v[124:127], v[196:197], off
	s_mov_b32 s4, s20
	v_lshl_add_u64 v[198:199], v[12:13], 0, s[4:5]
	global_load_dwordx4 v[132:135], v[198:199], off
	s_mov_b32 s4, s21
	v_lshl_add_u64 v[196:197], v[12:13], 0, s[4:5]
	global_load_dwordx4 v[136:139], v[196:197], off
	s_mov_b32 s4, s22
	v_lshl_add_u64 v[198:199], v[12:13], 0, s[4:5]
	global_load_dwordx4 v[140:143], v[198:199], off
	s_mov_b32 s4, s23
	v_lshl_add_u64 v[196:197], v[12:13], 0, s[4:5]
	global_load_dwordx4 v[144:147], v[196:197], off
	s_mov_b32 s4, s24
	v_lshl_add_u64 v[198:199], v[12:13], 0, s[4:5]
	global_load_dwordx4 v[148:151], v[198:199], off
	s_mov_b32 s4, s25
	v_lshl_add_u64 v[196:197], v[12:13], 0, s[4:5]
	global_load_dwordx4 v[152:155], v[196:197], off
	s_mov_b32 s4, s26
	v_lshl_add_u64 v[198:199], v[12:13], 0, s[4:5]
	global_load_dwordx4 v[156:159], v[198:199], off
	s_mov_b32 s4, s27
	v_lshl_add_u64 v[196:197], v[12:13], 0, s[4:5]
	global_load_dwordx4 v[164:167], v[196:197], off
	s_mov_b32 s4, s28
	v_lshl_add_u64 v[198:199], v[12:13], 0, s[4:5]
	global_load_dwordx4 v[168:171], v[198:199], off
	s_mov_b32 s4, s29
	v_lshl_add_u64 v[196:197], v[12:13], 0, s[4:5]
	global_load_dwordx4 v[172:175], v[196:197], off
	s_mov_b32 s4, s30
	v_lshl_add_u64 v[198:199], v[12:13], 0, s[4:5]
	global_load_dwordx4 v[180:183], v[198:199], off
	s_mov_b32 s4, s31
	v_lshl_add_u64 v[196:197], v[12:13], 0, s[4:5]
	global_load_dwordx4 v[184:187], v[196:197], off
	s_mov_b32 s4, s34
	v_lshl_add_u64 v[198:199], v[12:13], 0, s[4:5]
	global_load_dwordx4 v[188:191], v[198:199], off
	s_or_b32 s7, s7, s2
	s_lshl_b32 s6, s6, 7
	s_lshl_b32 s7, s7, 4
	s_add_i32 s6, s7, s6
	s_waitcnt vmcnt(30)
	v_pk_add_f32 v[0:1], v[52:53], v[56:57]
	v_pk_add_f32 v[2:3], v[54:55], v[58:59]
	s_waitcnt vmcnt(29)
	v_pk_add_f32 v[0:1], v[0:1], v[60:61]
	v_pk_add_f32 v[2:3], v[2:3], v[62:63]
	s_waitcnt vmcnt(28)
	v_pk_add_f32 v[0:1], v[0:1], v[64:65]
	v_pk_add_f32 v[2:3], v[2:3], v[66:67]
	s_waitcnt vmcnt(27)
	v_pk_add_f32 v[0:1], v[0:1], v[68:69]
	v_pk_add_f32 v[2:3], v[2:3], v[70:71]
	s_waitcnt vmcnt(26)
	v_pk_add_f32 v[0:1], v[0:1], v[72:73]
	v_pk_add_f32 v[2:3], v[2:3], v[74:75]
	s_waitcnt vmcnt(25)
	v_pk_add_f32 v[0:1], v[0:1], v[76:77]
	v_pk_add_f32 v[2:3], v[2:3], v[78:79]
	s_waitcnt vmcnt(24)
	v_pk_add_f32 v[0:1], v[0:1], v[80:81]
	v_pk_add_f32 v[2:3], v[2:3], v[82:83]
	s_waitcnt vmcnt(22)
	v_pk_add_f32 v[4:5], v[84:85], v[88:89]
	v_pk_add_f32 v[6:7], v[86:87], v[90:91]
	s_waitcnt vmcnt(21)
	v_pk_add_f32 v[4:5], v[4:5], v[92:93]
	v_pk_add_f32 v[6:7], v[6:7], v[94:95]
	s_waitcnt vmcnt(20)
	v_pk_add_f32 v[4:5], v[4:5], v[96:97]
	v_pk_add_f32 v[6:7], v[6:7], v[98:99]
	s_waitcnt vmcnt(19)
	v_pk_add_f32 v[4:5], v[4:5], v[100:101]
	v_pk_add_f32 v[6:7], v[6:7], v[102:103]
	s_waitcnt vmcnt(18)
	v_pk_add_f32 v[4:5], v[4:5], v[104:105]
	v_pk_add_f32 v[6:7], v[6:7], v[106:107]
	s_waitcnt vmcnt(17)
	v_pk_add_f32 v[4:5], v[4:5], v[108:109]
	v_pk_add_f32 v[6:7], v[6:7], v[110:111]
	s_waitcnt vmcnt(16)
	v_pk_add_f32 v[4:5], v[4:5], v[112:113]
	v_pk_add_f32 v[6:7], v[6:7], v[114:115]
	s_waitcnt vmcnt(14)
	v_pk_add_f32 v[8:9], v[116:117], v[120:121]
	v_pk_add_f32 v[10:11], v[118:119], v[122:123]
	s_waitcnt vmcnt(13)
	v_pk_add_f32 v[8:9], v[8:9], v[124:125]
	v_pk_add_f32 v[10:11], v[10:11], v[126:127]
	s_waitcnt vmcnt(12)
	v_pk_add_f32 v[8:9], v[8:9], v[132:133]
	v_pk_add_f32 v[10:11], v[10:11], v[134:135]
	s_waitcnt vmcnt(11)
	v_pk_add_f32 v[8:9], v[8:9], v[136:137]
	v_pk_add_f32 v[10:11], v[10:11], v[138:139]
	s_waitcnt vmcnt(10)
	v_pk_add_f32 v[8:9], v[8:9], v[140:141]
	v_pk_add_f32 v[10:11], v[10:11], v[142:143]
	s_waitcnt vmcnt(9)
	v_pk_add_f32 v[8:9], v[8:9], v[144:145]
	v_pk_add_f32 v[10:11], v[10:11], v[146:147]
	s_waitcnt vmcnt(8)
	v_pk_add_f32 v[8:9], v[8:9], v[148:149]
	v_pk_add_f32 v[10:11], v[10:11], v[150:151]
	s_waitcnt vmcnt(6)
	v_pk_add_f32 v[12:13], v[152:153], v[156:157]
	v_pk_add_f32 v[14:15], v[154:155], v[158:159]
	s_waitcnt vmcnt(5)
	v_pk_add_f32 v[12:13], v[12:13], v[164:165]
	v_pk_add_f32 v[14:15], v[14:15], v[166:167]
	s_waitcnt vmcnt(4)
	v_pk_add_f32 v[12:13], v[12:13], v[168:169]
	v_pk_add_f32 v[14:15], v[14:15], v[170:171]
	s_waitcnt vmcnt(3)
	v_pk_add_f32 v[12:13], v[12:13], v[172:173]
	v_pk_add_f32 v[14:15], v[14:15], v[174:175]
	s_waitcnt vmcnt(2)
	v_pk_add_f32 v[12:13], v[12:13], v[180:181]
	v_pk_add_f32 v[14:15], v[14:15], v[182:183]
	s_waitcnt vmcnt(1)
	v_pk_add_f32 v[12:13], v[12:13], v[184:185]
	v_pk_add_f32 v[14:15], v[14:15], v[186:187]
	s_waitcnt vmcnt(0)
	v_pk_add_f32 v[12:13], v[12:13], v[188:189]
	v_pk_add_f32 v[14:15], v[14:15], v[190:191]
	s_lshl_b32 s4, s17, 8
	s_add_i32 s4, s6, s4
	s_mov_b64 s[6:7], -1
	s_cmp_gt_i32 s16, 13
	v_or_b32_e32 v20, s4, v162
	s_cbranch_scc1 .LBB0_390
	s_and_b64 vcc, exec, s[6:7]
	s_cbranch_vccz .LBB0_383
	s_branch .LBB0_401
